# attention tile loop and SSD-out stage-3 loop without the per-iteration s_setprio alternation for waves 4-7 (all waves stay at priority 0); on top of v23
# speedup vs baseline: 1.0005x; 1.0005x over previous
; __device__ __forceinline__ void attn_unit(Frame& F, const Ptrs& P, int u, int u_next, bf16x8 (&qa)[4], ScanRider& R) {
;     ...
;     for (int jj = 0; jj < (dry ? PROBE_ATT_TRIPS : 5); ++jj) {
;         const int j = jlo + jj;
;         if (wid >= 4) { if (jj & 1) __builtin_amdgcn_s_setprio(0); else __builtin_amdgcn_s_setprio(1); }
.LBB0_654:
	s_andn2_b64 vcc, exec, s[4:5]
	s_cbranch_vccnz .LBB0_656
	s_setprio 0

; template <class Wait>
; __device__ __forceinline__ void out_unit(Frame& F, const Ptrs& P, int b, int c, int g, const Wait& wait) {
;     ...
;         for (int ks = 0; ks < 8; ++ks) {
;             if (wid >= 4) { if (ks & 1) __builtin_amdgcn_s_setprio(0); else __builtin_amdgcn_s_setprio(1); }
.LBB0_747:
	s_andn2_b64 vcc, exec, s[0:1]
	s_cbranch_vccnz .LBB0_749
	s_setprio 0
